# all three GEMM K-loops: LDS-DMA issues interleaved between the fragment ds_reads in every load segment (plus SGPR-base DMA addressing, hoisted LDS bases)
# speedup vs baseline: 1.0335x; 1.0049x over previous
; #define PG8_STAGE(bufoff, gbase, voff) do { _Pragma("unroll") for (int _i = 0; _i < 2; ++_i) \
;         __builtin_amdgcn_global_load_lds((const unsigned*)((const char*)(gbase) + (voff)[_i]), (PG8_LAS unsigned*)(lds + (bufoff) + ldsw + _i * 8192), 16, 0, 0); } while (0)
; #define PG8_LDA(dst, b, h) do { _Pragma("unroll") for (int m = 0; m < 4; ++m) _Pragma("unroll") for (int k = 0; k < 2; ++k) dst[m][k] = *(const PG8_LAS bf16x8*)(lds + PG8_SA(b, h) + aoff + m * 2048 + k * 1024); } while (0)
; #define PG8_LDB(dst, b, h) do { _Pragma("unroll") for (int n = 0; n < 2; ++n) _Pragma("unroll") for (int k = 0; k < 2; ++k) dst[n][k] = *(const PG8_LAS bf16x8*)(lds + PG8_SB(b, h) + boff + n * 2048 + k * 1024); } while (0)
; #define PG8_MMA(ai, bj, At, Bt) do { __builtin_amdgcn_s_setprio(1); _Pragma("unroll") for (int m = 0; m < 4; ++m) _Pragma("unroll") for (int n = 0; n < 2; ++n) _Pragma("unroll") for (int k = 0; k < 2; ++k) \
;         acc[ai][bj][m][n] = __builtin_amdgcn_mfma_f32_16x16x32_bf16(Bt[n][k], At[m][k], acc[ai][bj][m][n], 0, 0, 0); __builtin_amdgcn_s_setprio(0); } while (0)
; #define PG8_WAIT_V(n) asm volatile("s_waitcnt vmcnt(" #n ")" ::: "memory")
; #define PG8_WAIT_L(n) asm volatile("s_waitcnt lgkmcnt(" #n ")" ::: "memory")
; #define PG8_BAR __builtin_amdgcn_s_barrier()
; #define PG8_SCHED __builtin_amdgcn_sched_barrier(0)
; template <class Epi, class Sched, bool ALIGN_EPI = false, bool SP2 = false>
; __device__ __forceinline__ void gemm_phase(PG8_LAS unsigned char* lds, const Gemm g, const Sched& S, const Epi& E) {
;     ...
;             PG8_LDB(B0, 0, 0); PG8_LDB(B1, 0, 1); PG8_SCHED; PG8_LDA(At, 0, 0); PG8_STAGE(PG8_SA(1, 1), a1 + hstep, voffA);
;             PG8_WAIT_V(8); PG8_WAIT_L(0); PG8_BAR; PG8_MMA(0, 0, At, B0); PG8_MMA(0, 1, At, B1); PG8_BAR; PG8_SCHED;
;             PG8_LDA(At, 0, 1); PG8_STAGE(PG8_SB(0, 0), b2, voffB); PG8_STAGE(PG8_SB(0, 1), b2 + hstep, voffB); PG8_STAGE(PG8_SA(0, 0), a2, voffA);
;             PG8_WAIT_V(8); PG8_WAIT_L(0); PG8_BAR; PG8_MMA(1, 0, At, B0); PG8_MMA(1, 1, At, B1); PG8_BAR; PG8_SCHED;
.LBB0_82:
	s_add_i32 s28, s46, 2
	s_add_u32 s29, s44, 0x80
	s_addc_u32 s47, s45, 0
	s_add_i32 s12, 0, 0x10000
	s_cmp_eq_u32 s24, s46
	s_cselect_b32 s47, s65, s47
	s_cselect_b32 s46, s92, s29
	s_cselect_b32 s73, s61, vcc_hi
	s_cselect_b32 s72, s93, vcc_lo
	s_add_i32 s29, 0, 0x14000
	s_add_i32 m0, s70, 0xc000
	ds_read_b128 v[56:59], v204
	global_load_lds_dwordx4 v182, s[44:45]
	ds_read_b128 v[60:63], v204 offset:1024
	ds_read_b128 v[64:67], v204 offset:2048
	ds_read_b128 v[68:71], v204 offset:3072
	ds_read_b128 v[144:147], v205
	ds_read_b128 v[148:151], v205 offset:1024
	ds_read_b128 v[152:155], v205 offset:2048
	ds_read_b128 v[156:159], v205 offset:3072
	s_add_i32 m0, s70, 0xe000
	ds_read_b128 v[160:163], v237
	global_load_lds_dwordx4 v184, s[44:45]
	ds_read_b128 v[164:167], v237 offset:1024
	ds_read_b128 v[168:171], v237 offset:2048
	ds_read_b128 v[172:175], v237 offset:3072
	ds_read_b128 v[186:189], v237 offset:4096
	ds_read_b128 v[190:193], v237 offset:5120
	ds_read_b128 v[196:199], v237 offset:6144
	ds_read_b128 v[200:203], v237 offset:7168
	s_waitcnt vmcnt(8)
	s_waitcnt lgkmcnt(0)
	s_barrier
	s_setprio 1
	s_waitcnt lgkmcnt(0)
	v_mfma_f32_16x16x32_bf16 v[140:143], v[56:59], v[160:163], v[140:143]
	v_mfma_f32_16x16x32_bf16 v[136:139], v[64:67], v[160:163], v[136:139]
	v_mfma_f32_16x16x32_bf16 v[124:127], v[56:59], v[168:171], v[124:127]
	v_mfma_f32_16x16x32_bf16 v[120:123], v[64:67], v[168:171], v[120:123]
	v_mfma_f32_16x16x32_bf16 v[108:111], v[56:59], v[186:189], v[108:111]
	v_mfma_f32_16x16x32_bf16 v[104:107], v[64:67], v[186:189], v[104:107]
	v_mfma_f32_16x16x32_bf16 v[92:95], v[56:59], v[196:199], v[92:95]
	v_mfma_f32_16x16x32_bf16 v[88:91], v[64:67], v[196:199], v[88:91]
	v_mfma_f32_16x16x32_bf16 v[140:143], v[60:63], v[164:167], v[140:143]
	v_mfma_f32_16x16x32_bf16 v[136:139], v[68:71], v[164:167], v[136:139]
	v_mfma_f32_16x16x32_bf16 v[124:127], v[60:63], v[172:175], v[124:127]
	v_mfma_f32_16x16x32_bf16 v[120:123], v[68:71], v[172:175], v[120:123]
	v_mfma_f32_16x16x32_bf16 v[108:111], v[60:63], v[190:193], v[108:111]
	v_mfma_f32_16x16x32_bf16 v[104:107], v[68:71], v[190:193], v[104:107]
	v_mfma_f32_16x16x32_bf16 v[92:95], v[60:63], v[200:203], v[92:95]
	v_mfma_f32_16x16x32_bf16 v[88:91], v[68:71], v[200:203], v[88:91]
	s_setprio 0
	s_setprio 1
	v_mfma_f32_16x16x32_bf16 v[132:135], v[144:147], v[160:163], v[132:135]
	v_mfma_f32_16x16x32_bf16 v[128:131], v[152:155], v[160:163], v[128:131]
	v_mfma_f32_16x16x32_bf16 v[116:119], v[144:147], v[168:171], v[116:119]
	v_mfma_f32_16x16x32_bf16 v[112:115], v[152:155], v[168:171], v[112:115]
	v_mfma_f32_16x16x32_bf16 v[100:103], v[144:147], v[186:189], v[100:103]
	v_mfma_f32_16x16x32_bf16 v[96:99], v[152:155], v[186:189], v[96:99]
	v_mfma_f32_16x16x32_bf16 v[84:87], v[144:147], v[196:199], v[84:87]
	v_mfma_f32_16x16x32_bf16 v[80:83], v[152:155], v[196:199], v[80:83]
	v_mfma_f32_16x16x32_bf16 v[132:135], v[148:151], v[164:167], v[132:135]
	v_mfma_f32_16x16x32_bf16 v[128:131], v[156:159], v[164:167], v[128:131]
	v_mfma_f32_16x16x32_bf16 v[116:119], v[148:151], v[172:175], v[116:119]
	v_mfma_f32_16x16x32_bf16 v[112:115], v[156:159], v[172:175], v[112:115]
	v_mfma_f32_16x16x32_bf16 v[100:103], v[148:151], v[190:193], v[100:103]
	v_mfma_f32_16x16x32_bf16 v[96:99], v[156:159], v[190:193], v[96:99]
	v_mfma_f32_16x16x32_bf16 v[84:87], v[148:151], v[200:203], v[84:87]
	v_mfma_f32_16x16x32_bf16 v[80:83], v[156:159], v[200:203], v[80:83]
	s_setprio 0
	s_barrier
	s_add_i32 s12, s12, s2
	s_mov_b32 m0, s12
	ds_read_b128 v[160:163], v237 offset:16384
	global_load_lds_dwordx4 v194, s[72:73]
	s_add_i32 m0, s12, 0x2000
	s_add_u32 s98, s72, 0x80
	s_addc_u32 s99, s73, 0
	s_add_i32 s12, s29, s2
	ds_read_b128 v[164:167], v237 offset:17408
	global_load_lds_dwordx4 v176, s[72:73]
	s_mov_b32 m0, s12
	s_add_u32 s72, s72, s22
	s_addc_u32 s73, s73, 0
	s_add_u32 s100, s46, 0x80
	s_addc_u32 s101, s47, 0
	ds_read_b128 v[168:171], v237 offset:18432
	global_load_lds_dwordx4 v194, s[72:73]
	s_add_i32 m0, s12, 0x2000
	ds_read_b128 v[172:175], v237 offset:19456
	global_load_lds_dwordx4 v176, s[72:73]
	s_mov_b32 m0, s70
	ds_read_b128 v[186:189], v237 offset:20480
	global_load_lds_dwordx4 v180, s[46:47]
	s_mov_b32 m0, s71
	ds_read_b128 v[190:193], v237 offset:21504
	global_load_lds_dwordx4 v178, s[46:47]
	ds_read_b128 v[196:199], v237 offset:22528
	ds_read_b128 v[200:203], v237 offset:23552
	s_waitcnt vmcnt(8)
	s_waitcnt lgkmcnt(0)
	s_barrier
	s_setprio 1
	s_waitcnt lgkmcnt(0)
	v_mfma_f32_16x16x32_bf16 v[76:79], v[56:59], v[160:163], v[76:79]
	v_mfma_f32_16x16x32_bf16 v[72:75], v[64:67], v[160:163], v[72:75]
	v_mfma_f32_16x16x32_bf16 v[44:47], v[56:59], v[168:171], v[44:47]
	v_mfma_f32_16x16x32_bf16 v[40:43], v[64:67], v[168:171], v[40:43]
	v_mfma_f32_16x16x32_bf16 v[28:31], v[56:59], v[186:189], v[28:31]
	v_mfma_f32_16x16x32_bf16 v[24:27], v[64:67], v[186:189], v[24:27]
	v_mfma_f32_16x16x32_bf16 v[12:15], v[56:59], v[196:199], v[12:15]
	v_mfma_f32_16x16x32_bf16 v[8:11], v[64:67], v[196:199], v[8:11]
	v_mfma_f32_16x16x32_bf16 v[76:79], v[60:63], v[164:167], v[76:79]
	v_mfma_f32_16x16x32_bf16 v[72:75], v[68:71], v[164:167], v[72:75]
	v_mfma_f32_16x16x32_bf16 v[44:47], v[60:63], v[172:175], v[44:47]
	v_mfma_f32_16x16x32_bf16 v[40:43], v[68:71], v[172:175], v[40:43]
	v_mfma_f32_16x16x32_bf16 v[28:31], v[60:63], v[190:193], v[28:31]
	v_mfma_f32_16x16x32_bf16 v[24:27], v[68:71], v[190:193], v[24:27]
	v_mfma_f32_16x16x32_bf16 v[12:15], v[60:63], v[200:203], v[12:15]
	v_mfma_f32_16x16x32_bf16 v[8:11], v[68:71], v[200:203], v[8:11]
	s_setprio 0
	s_setprio 1
	v_mfma_f32_16x16x32_bf16 v[52:55], v[144:147], v[160:163], v[52:55]
	v_mfma_f32_16x16x32_bf16 v[48:51], v[152:155], v[160:163], v[48:51]
	v_mfma_f32_16x16x32_bf16 v[36:39], v[144:147], v[168:171], v[36:39]
	v_mfma_f32_16x16x32_bf16 v[32:35], v[152:155], v[168:171], v[32:35]
	v_mfma_f32_16x16x32_bf16 v[20:23], v[144:147], v[186:189], v[20:23]
	v_mfma_f32_16x16x32_bf16 v[16:19], v[152:155], v[186:189], v[16:19]
	v_mfma_f32_16x16x32_bf16 v[4:7], v[144:147], v[196:199], v[4:7]
	v_mfma_f32_16x16x32_bf16 v[0:3], v[152:155], v[196:199], v[0:3]
	v_mfma_f32_16x16x32_bf16 v[52:55], v[148:151], v[164:167], v[52:55]
	v_mfma_f32_16x16x32_bf16 v[48:51], v[156:159], v[164:167], v[48:51]
	v_mfma_f32_16x16x32_bf16 v[36:39], v[148:151], v[172:175], v[36:39]
	v_mfma_f32_16x16x32_bf16 v[32:35], v[156:159], v[172:175], v[32:35]
	v_mfma_f32_16x16x32_bf16 v[20:23], v[148:151], v[190:193], v[20:23]
	v_mfma_f32_16x16x32_bf16 v[16:19], v[156:159], v[190:193], v[16:19]
	v_mfma_f32_16x16x32_bf16 v[4:7], v[148:151], v[200:203], v[4:7]
	v_mfma_f32_16x16x32_bf16 v[0:3], v[156:159], v[200:203], v[0:3]
	s_setprio 0
	s_barrier
; #define PG8_STAGE(bufoff, gbase, voff) do { _Pragma("unroll") for (int _i = 0; _i < 2; ++_i) \
;         __builtin_amdgcn_global_load_lds((const unsigned*)((const char*)(gbase) + (voff)[_i]), (PG8_LAS unsigned*)(lds + (bufoff) + ldsw + _i * 8192), 16, 0, 0); } while (0)
; #define PG8_LDA(dst, b, h) do { _Pragma("unroll") for (int m = 0; m < 4; ++m) _Pragma("unroll") for (int k = 0; k < 2; ++k) dst[m][k] = *(const PG8_LAS bf16x8*)(lds + PG8_SA(b, h) + aoff + m * 2048 + k * 1024); } while (0)
; #define PG8_LDB(dst, b, h) do { _Pragma("unroll") for (int n = 0; n < 2; ++n) _Pragma("unroll") for (int k = 0; k < 2; ++k) dst[n][k] = *(const PG8_LAS bf16x8*)(lds + PG8_SB(b, h) + boff + n * 2048 + k * 1024); } while (0)
; #define PG8_MMA(ai, bj, At, Bt) do { __builtin_amdgcn_s_setprio(1); _Pragma("unroll") for (int m = 0; m < 4; ++m) _Pragma("unroll") for (int n = 0; n < 2; ++n) _Pragma("unroll") for (int k = 0; k < 2; ++k) \
;         acc[ai][bj][m][n] = __builtin_amdgcn_mfma_f32_16x16x32_bf16(Bt[n][k], At[m][k], acc[ai][bj][m][n], 0, 0, 0); __builtin_amdgcn_s_setprio(0); } while (0)
; #define PG8_WAIT_V(n) asm volatile("s_waitcnt vmcnt(" #n ")" ::: "memory")
; #define PG8_WAIT_L(n) asm volatile("s_waitcnt lgkmcnt(" #n ")" ::: "memory")
; #define PG8_BAR __builtin_amdgcn_s_barrier()
; #define PG8_SCHED __builtin_amdgcn_sched_barrier(0)
; template <class Epi, class Sched, bool ALIGN_EPI = false, bool SP2 = false>
; __device__ __forceinline__ void gemm_phase(PG8_LAS unsigned char* lds, const Gemm g, const Sched& S, const Epi& E) {
;     ...
;             PG8_LDB(B0, 1, 0); PG8_LDB(B1, 1, 1); PG8_SCHED; PG8_LDA(At, 1, 0); PG8_STAGE(PG8_SA(0, 1), a2 + hstep, voffA);
;             PG8_WAIT_V(8); PG8_WAIT_L(0); PG8_BAR; PG8_MMA(0, 0, At, B0); PG8_MMA(0, 1, At, B1); PG8_BAR; PG8_SCHED;
;             PG8_LDA(At, 1, 1); PG8_STAGE(PG8_SB(1, 0), b3, voffB); PG8_STAGE(PG8_SB(1, 1), b3 + hstep, voffB); PG8_STAGE(PG8_SA(1, 0), a3, voffA);
;             PG8_WAIT_V(8); PG8_WAIT_L(0); PG8_BAR; PG8_MMA(1, 0, At, B0); PG8_MMA(1, 1, At, B1); PG8_BAR; PG8_SCHED;
	s_add_i32 s12, 0, 0x18000
	s_add_i32 s29, 0, 0x1c000
	s_add_u32 s46, s46, s22
	s_addc_u32 s47, s47, 0
	s_mov_b32 m0, s76
	ds_read_b128 v[56:59], v206
	global_load_lds_dwordx4 v180, s[46:47]
	ds_read_b128 v[60:63], v206 offset:1024
	ds_read_b128 v[64:67], v206 offset:2048
	ds_read_b128 v[68:71], v206 offset:3072
	ds_read_b128 v[144:147], v207
	ds_read_b128 v[148:151], v207 offset:1024
	ds_read_b128 v[152:155], v207 offset:2048
	ds_read_b128 v[156:159], v207 offset:3072
	s_mov_b32 m0, s77
	ds_read_b128 v[160:163], v237 offset:32768
	global_load_lds_dwordx4 v178, s[46:47]
	ds_read_b128 v[164:167], v237 offset:33792
	ds_read_b128 v[168:171], v237 offset:34816
	ds_read_b128 v[172:175], v237 offset:35840
	ds_read_b128 v[186:189], v237 offset:36864
	ds_read_b128 v[190:193], v237 offset:37888
	ds_read_b128 v[196:199], v237 offset:38912
	ds_read_b128 v[200:203], v237 offset:39936
	s_waitcnt vmcnt(8)
	s_waitcnt lgkmcnt(0)
	s_barrier
	s_setprio 1
	s_waitcnt lgkmcnt(0)
	v_mfma_f32_16x16x32_bf16 v[140:143], v[56:59], v[160:163], v[140:143]
	v_mfma_f32_16x16x32_bf16 v[136:139], v[64:67], v[160:163], v[136:139]
	v_mfma_f32_16x16x32_bf16 v[124:127], v[56:59], v[168:171], v[124:127]
	v_mfma_f32_16x16x32_bf16 v[120:123], v[64:67], v[168:171], v[120:123]
	v_mfma_f32_16x16x32_bf16 v[108:111], v[56:59], v[186:189], v[108:111]
	v_mfma_f32_16x16x32_bf16 v[104:107], v[64:67], v[186:189], v[104:107]
	v_mfma_f32_16x16x32_bf16 v[92:95], v[56:59], v[196:199], v[92:95]
	v_mfma_f32_16x16x32_bf16 v[88:91], v[64:67], v[196:199], v[88:91]
	v_mfma_f32_16x16x32_bf16 v[140:143], v[60:63], v[164:167], v[140:143]
	v_mfma_f32_16x16x32_bf16 v[136:139], v[68:71], v[164:167], v[136:139]
	v_mfma_f32_16x16x32_bf16 v[124:127], v[60:63], v[172:175], v[124:127]
	v_mfma_f32_16x16x32_bf16 v[120:123], v[68:71], v[172:175], v[120:123]
	v_mfma_f32_16x16x32_bf16 v[108:111], v[60:63], v[190:193], v[108:111]
	v_mfma_f32_16x16x32_bf16 v[104:107], v[68:71], v[190:193], v[104:107]
	v_mfma_f32_16x16x32_bf16 v[92:95], v[60:63], v[200:203], v[92:95]
	v_mfma_f32_16x16x32_bf16 v[88:91], v[68:71], v[200:203], v[88:91]
	s_setprio 0
	s_setprio 1
	v_mfma_f32_16x16x32_bf16 v[132:135], v[144:147], v[160:163], v[132:135]
	v_mfma_f32_16x16x32_bf16 v[128:131], v[152:155], v[160:163], v[128:131]
	v_mfma_f32_16x16x32_bf16 v[116:119], v[144:147], v[168:171], v[116:119]
	v_mfma_f32_16x16x32_bf16 v[112:115], v[152:155], v[168:171], v[112:115]
	v_mfma_f32_16x16x32_bf16 v[100:103], v[144:147], v[186:189], v[100:103]
	v_mfma_f32_16x16x32_bf16 v[96:99], v[152:155], v[186:189], v[96:99]
	v_mfma_f32_16x16x32_bf16 v[84:87], v[144:147], v[196:199], v[84:87]
	v_mfma_f32_16x16x32_bf16 v[80:83], v[152:155], v[196:199], v[80:83]
	v_mfma_f32_16x16x32_bf16 v[132:135], v[148:151], v[164:167], v[132:135]
	v_mfma_f32_16x16x32_bf16 v[128:131], v[156:159], v[164:167], v[128:131]
	v_mfma_f32_16x16x32_bf16 v[116:119], v[148:151], v[172:175], v[116:119]
	v_mfma_f32_16x16x32_bf16 v[112:115], v[156:159], v[172:175], v[112:115]
	v_mfma_f32_16x16x32_bf16 v[100:103], v[148:151], v[190:193], v[100:103]
	v_mfma_f32_16x16x32_bf16 v[96:99], v[156:159], v[190:193], v[96:99]
	v_mfma_f32_16x16x32_bf16 v[84:87], v[148:151], v[200:203], v[84:87]
	v_mfma_f32_16x16x32_bf16 v[80:83], v[156:159], v[200:203], v[80:83]
	s_setprio 0
	s_barrier
	s_add_i32 s12, s12, s2
	s_mov_b32 m0, s12
	ds_read_b128 v[160:163], v237 offset:49152
	global_load_lds_dwordx4 v194, s[98:99]
	s_add_i32 m0, s12, 0x2000
	s_add_i32 s12, s29, s2
	s_add_u32 s72, s72, 0x80
	s_addc_u32 s73, s73, 0
	ds_read_b128 v[164:167], v237 offset:50176
	global_load_lds_dwordx4 v176, s[98:99]
	s_mov_b32 m0, s12
	ds_read_b128 v[168:171], v237 offset:51200
	global_load_lds_dwordx4 v194, s[72:73]
	s_add_i32 m0, s12, 0x2000
	ds_read_b128 v[172:175], v237 offset:52224
	global_load_lds_dwordx4 v176, s[72:73]
	s_mov_b32 m0, s48
	ds_read_b128 v[186:189], v237 offset:53248
	global_load_lds_dwordx4 v180, s[100:101]
	s_mov_b32 m0, s49
	ds_read_b128 v[190:193], v237 offset:54272
	global_load_lds_dwordx4 v178, s[100:101]
	ds_read_b128 v[196:199], v237 offset:55296
	ds_read_b128 v[200:203], v237 offset:56320
	s_waitcnt vmcnt(8)
	s_waitcnt lgkmcnt(0)
	s_barrier
	s_setprio 1
	s_waitcnt lgkmcnt(0)
	v_mfma_f32_16x16x32_bf16 v[76:79], v[56:59], v[160:163], v[76:79]
	v_mfma_f32_16x16x32_bf16 v[72:75], v[64:67], v[160:163], v[72:75]
	v_mfma_f32_16x16x32_bf16 v[44:47], v[56:59], v[168:171], v[44:47]
	v_mfma_f32_16x16x32_bf16 v[40:43], v[64:67], v[168:171], v[40:43]
	v_mfma_f32_16x16x32_bf16 v[28:31], v[56:59], v[186:189], v[28:31]
	v_mfma_f32_16x16x32_bf16 v[24:27], v[64:67], v[186:189], v[24:27]
	v_mfma_f32_16x16x32_bf16 v[12:15], v[56:59], v[196:199], v[12:15]
	v_mfma_f32_16x16x32_bf16 v[8:11], v[64:67], v[196:199], v[8:11]
	v_mfma_f32_16x16x32_bf16 v[76:79], v[60:63], v[164:167], v[76:79]
	v_mfma_f32_16x16x32_bf16 v[72:75], v[68:71], v[164:167], v[72:75]
	v_mfma_f32_16x16x32_bf16 v[44:47], v[60:63], v[172:175], v[44:47]
	v_mfma_f32_16x16x32_bf16 v[40:43], v[68:71], v[172:175], v[40:43]
	v_mfma_f32_16x16x32_bf16 v[28:31], v[60:63], v[190:193], v[28:31]
	v_mfma_f32_16x16x32_bf16 v[24:27], v[68:71], v[190:193], v[24:27]
	v_mfma_f32_16x16x32_bf16 v[12:15], v[60:63], v[200:203], v[12:15]
	v_mfma_f32_16x16x32_bf16 v[8:11], v[68:71], v[200:203], v[8:11]
	s_setprio 0
	s_setprio 1
	v_mfma_f32_16x16x32_bf16 v[52:55], v[144:147], v[160:163], v[52:55]
	v_mfma_f32_16x16x32_bf16 v[48:51], v[152:155], v[160:163], v[48:51]
	v_mfma_f32_16x16x32_bf16 v[36:39], v[144:147], v[168:171], v[36:39]
	v_mfma_f32_16x16x32_bf16 v[32:35], v[152:155], v[168:171], v[32:35]
	v_mfma_f32_16x16x32_bf16 v[20:23], v[144:147], v[186:189], v[20:23]
	v_mfma_f32_16x16x32_bf16 v[16:19], v[152:155], v[186:189], v[16:19]
	v_mfma_f32_16x16x32_bf16 v[4:7], v[144:147], v[196:199], v[4:7]
	v_mfma_f32_16x16x32_bf16 v[0:3], v[152:155], v[196:199], v[0:3]
	v_mfma_f32_16x16x32_bf16 v[52:55], v[148:151], v[164:167], v[52:55]
	v_mfma_f32_16x16x32_bf16 v[48:51], v[156:159], v[164:167], v[48:51]
	v_mfma_f32_16x16x32_bf16 v[36:39], v[148:151], v[172:175], v[36:39]
	v_mfma_f32_16x16x32_bf16 v[32:35], v[156:159], v[172:175], v[32:35]
	v_mfma_f32_16x16x32_bf16 v[20:23], v[148:151], v[190:193], v[20:23]
	v_mfma_f32_16x16x32_bf16 v[16:19], v[156:159], v[190:193], v[16:19]
	v_mfma_f32_16x16x32_bf16 v[4:7], v[148:151], v[200:203], v[4:7]
	v_mfma_f32_16x16x32_bf16 v[0:3], v[156:159], v[200:203], v[0:3]
	s_setprio 0
	s_barrier
	s_add_u32 s44, s44, 0x100
	s_addc_u32 s45, s45, 0
	s_add_u32 vcc_lo, vcc_lo, 0x100
	s_addc_u32 vcc_hi, vcc_hi, 0
	s_cmp_ge_u32 s28, s7
	s_mov_b32 s46, s28
	s_cbranch_scc0 .LBB0_82
	s_and_b64 vcc, exec, s[50:51]
	s_cbranch_vccz .LBB0_85
	s_barrier

; #define PG8_STAGE(bufoff, gbase, voff) do { _Pragma("unroll") for (int _i = 0; _i < 2; ++_i) \
;         __builtin_amdgcn_global_load_lds((const unsigned*)((const char*)(gbase) + (voff)[_i]), (PG8_LAS unsigned*)(lds + (bufoff) + ldsw + _i * 8192), 16, 0, 0); } while (0)
; #define PG8_LDA(dst, b, h) do { _Pragma("unroll") for (int m = 0; m < 4; ++m) _Pragma("unroll") for (int k = 0; k < 2; ++k) dst[m][k] = *(const PG8_LAS bf16x8*)(lds + PG8_SA(b, h) + aoff + m * 2048 + k * 1024); } while (0)
; #define PG8_LDB(dst, b, h) do { _Pragma("unroll") for (int n = 0; n < 2; ++n) _Pragma("unroll") for (int k = 0; k < 2; ++k) dst[n][k] = *(const PG8_LAS bf16x8*)(lds + PG8_SB(b, h) + boff + n * 2048 + k * 1024); } while (0)
; #define PG8_MMA(ai, bj, At, Bt) do { __builtin_amdgcn_s_setprio(1); _Pragma("unroll") for (int m = 0; m < 4; ++m) _Pragma("unroll") for (int n = 0; n < 2; ++n) _Pragma("unroll") for (int k = 0; k < 2; ++k) \
;         acc[ai][bj][m][n] = __builtin_amdgcn_mfma_f32_16x16x32_bf16(Bt[n][k], At[m][k], acc[ai][bj][m][n], 0, 0, 0); __builtin_amdgcn_s_setprio(0); } while (0)
; #define PG8_WAIT_V(n) asm volatile("s_waitcnt vmcnt(" #n ")" ::: "memory")
; #define PG8_WAIT_L(n) asm volatile("s_waitcnt lgkmcnt(" #n ")" ::: "memory")
; #define PG8_BAR __builtin_amdgcn_s_barrier()
; #define PG8_SCHED __builtin_amdgcn_sched_barrier(0)
; template <class Epi, class Sched, bool ALIGN_EPI = false, bool SP2 = false>
; __device__ __forceinline__ void gemm_phase(PG8_LAS unsigned char* lds, const Gemm g, const Sched& S, const Epi& E) {
;     ...
;             PG8_LDB(B0, 0, 0); PG8_LDB(B1, 0, 1); PG8_SCHED; PG8_LDA(At, 0, 0); PG8_STAGE(PG8_SA(1, 1), a1 + hstep, voffA);
;             PG8_WAIT_V(8); PG8_WAIT_L(0); PG8_BAR; PG8_MMA(0, 0, At, B0); PG8_MMA(0, 1, At, B1); PG8_BAR; PG8_SCHED;
;             PG8_LDA(At, 0, 1); PG8_STAGE(PG8_SB(0, 0), b2, voffB); PG8_STAGE(PG8_SB(0, 1), b2 + hstep, voffB); PG8_STAGE(PG8_SA(0, 0), a2, voffA);
;             PG8_WAIT_V(8); PG8_WAIT_L(0); PG8_BAR; PG8_MMA(1, 0, At, B0); PG8_MMA(1, 1, At, B1); PG8_BAR; PG8_SCHED;
.LBB0_402:
	s_add_u32 s28, s26, 0xfff80080
	s_addc_u32 s29, s27, -1
	s_add_i32 s72, 0, 0x10000
	s_cmp_eq_u32 s88, 28
	s_cselect_b32 s49, s50, s29
	s_cselect_b32 s48, s51, s28
	s_cselect_b32 s47, s52, s61
	s_cselect_b32 s46, s53, s55
	s_add_i32 s73, 0, 0x14000
	s_add_i32 m0, s77, 0xc000
	ds_read_b128 v[32:35], v192
	global_load_lds_dwordx4 v156, s[26:27]
	ds_read_b128 v[36:39], v192 offset:1024
	ds_read_b128 v[40:43], v192 offset:2048
	ds_read_b128 v[44:47], v192 offset:3072
	ds_read_b128 v[160:163], v193
	ds_read_b128 v[164:167], v193 offset:1024
	ds_read_b128 v[168:171], v193 offset:2048
	ds_read_b128 v[176:179], v193 offset:3072
	s_add_i32 m0, s77, 0xe000
	ds_read_b128 v[180:183], v174
	global_load_lds_dwordx4 v158, s[26:27]
	ds_read_b128 v[184:187], v174 offset:1024
	ds_read_b128 v[188:191], v174 offset:2048
	ds_read_b128 v[196:199], v174 offset:3072
	ds_read_b128 v[200:203], v174 offset:4096
	ds_read_b128 v[204:207], v174 offset:5120
	ds_read_b128 v[208:211], v174 offset:6144
	ds_read_b128 v[234:237], v174 offset:7168
	s_waitcnt vmcnt(8)
	s_waitcnt lgkmcnt(0)
	s_barrier
	s_setprio 1
	s_waitcnt lgkmcnt(0)
	v_mfma_f32_16x16x32_bf16 v[140:143], v[32:35], v[180:183], v[140:143]
	v_mfma_f32_16x16x32_bf16 v[136:139], v[40:43], v[180:183], v[136:139]
	v_mfma_f32_16x16x32_bf16 v[124:127], v[32:35], v[188:191], v[124:127]
	v_mfma_f32_16x16x32_bf16 v[120:123], v[40:43], v[188:191], v[120:123]
	v_mfma_f32_16x16x32_bf16 v[108:111], v[32:35], v[200:203], v[108:111]
	v_mfma_f32_16x16x32_bf16 v[104:107], v[40:43], v[200:203], v[104:107]
	v_mfma_f32_16x16x32_bf16 v[92:95], v[32:35], v[208:211], v[92:95]
	v_mfma_f32_16x16x32_bf16 v[88:91], v[40:43], v[208:211], v[88:91]
	v_mfma_f32_16x16x32_bf16 v[140:143], v[36:39], v[184:187], v[140:143]
	v_mfma_f32_16x16x32_bf16 v[136:139], v[44:47], v[184:187], v[136:139]
	v_mfma_f32_16x16x32_bf16 v[124:127], v[36:39], v[196:199], v[124:127]
	v_mfma_f32_16x16x32_bf16 v[120:123], v[44:47], v[196:199], v[120:123]
	v_mfma_f32_16x16x32_bf16 v[108:111], v[36:39], v[204:207], v[108:111]
	v_mfma_f32_16x16x32_bf16 v[104:107], v[44:47], v[204:207], v[104:107]
	v_mfma_f32_16x16x32_bf16 v[92:95], v[36:39], v[234:237], v[92:95]
	v_mfma_f32_16x16x32_bf16 v[88:91], v[44:47], v[234:237], v[88:91]
	s_setprio 0
	s_setprio 1
	v_mfma_f32_16x16x32_bf16 v[132:135], v[160:163], v[180:183], v[132:135]
	v_mfma_f32_16x16x32_bf16 v[128:131], v[168:171], v[180:183], v[128:131]
	v_mfma_f32_16x16x32_bf16 v[116:119], v[160:163], v[188:191], v[116:119]
	v_mfma_f32_16x16x32_bf16 v[112:115], v[168:171], v[188:191], v[112:115]
	v_mfma_f32_16x16x32_bf16 v[100:103], v[160:163], v[200:203], v[100:103]
	v_mfma_f32_16x16x32_bf16 v[96:99], v[168:171], v[200:203], v[96:99]
	v_mfma_f32_16x16x32_bf16 v[84:87], v[160:163], v[208:211], v[84:87]
	v_mfma_f32_16x16x32_bf16 v[80:83], v[168:171], v[208:211], v[80:83]
	v_mfma_f32_16x16x32_bf16 v[132:135], v[164:167], v[184:187], v[132:135]
	v_mfma_f32_16x16x32_bf16 v[128:131], v[176:179], v[184:187], v[128:131]
	v_mfma_f32_16x16x32_bf16 v[116:119], v[164:167], v[196:199], v[116:119]
	v_mfma_f32_16x16x32_bf16 v[112:115], v[176:179], v[196:199], v[112:115]
	v_mfma_f32_16x16x32_bf16 v[100:103], v[164:167], v[204:207], v[100:103]
	v_mfma_f32_16x16x32_bf16 v[96:99], v[176:179], v[204:207], v[96:99]
	v_mfma_f32_16x16x32_bf16 v[84:87], v[164:167], v[234:237], v[84:87]
	v_mfma_f32_16x16x32_bf16 v[80:83], v[176:179], v[234:237], v[80:83]
	s_setprio 0
	s_barrier
	s_add_i32 s28, s72, s76
	s_mov_b32 m0, s28
	ds_read_b128 v[180:183], v174 offset:16384
	global_load_lds_dwordx4 v148, s[46:47]
	s_add_i32 m0, s28, 0x2000
	s_add_u32 s28, s46, 0x80000
	s_addc_u32 s29, s47, 0
	s_add_i32 s72, s73, s76
	ds_read_b128 v[184:187], v174 offset:17408
	global_load_lds_dwordx4 v144, s[46:47]
	s_mov_b32 m0, s72
	ds_read_b128 v[188:191], v174 offset:18432
	global_load_lds_dwordx4 v148, s[28:29]
	s_add_i32 m0, s72, 0x2000
	ds_read_b128 v[196:199], v174 offset:19456
	global_load_lds_dwordx4 v144, s[28:29]
	s_mov_b32 m0, s77
	ds_read_b128 v[200:203], v174 offset:20480
	global_load_lds_dwordx4 v150, s[48:49]
	s_mov_b32 m0, s79
	ds_read_b128 v[204:207], v174 offset:21504
	global_load_lds_dwordx4 v146, s[48:49]
	ds_read_b128 v[208:211], v174 offset:22528
	ds_read_b128 v[234:237], v174 offset:23552
	s_waitcnt vmcnt(8)
	s_waitcnt lgkmcnt(0)
	s_barrier
	s_setprio 1
	s_waitcnt lgkmcnt(0)
	v_mfma_f32_16x16x32_bf16 v[76:79], v[32:35], v[180:183], v[76:79]
	v_mfma_f32_16x16x32_bf16 v[72:75], v[40:43], v[180:183], v[72:75]
	v_mfma_f32_16x16x32_bf16 v[60:63], v[32:35], v[188:191], v[60:63]
	v_mfma_f32_16x16x32_bf16 v[56:59], v[40:43], v[188:191], v[56:59]
	v_mfma_f32_16x16x32_bf16 v[28:31], v[32:35], v[200:203], v[28:31]
	v_mfma_f32_16x16x32_bf16 v[24:27], v[40:43], v[200:203], v[24:27]
	v_mfma_f32_16x16x32_bf16 v[12:15], v[32:35], v[208:211], v[12:15]
	v_mfma_f32_16x16x32_bf16 v[8:11], v[40:43], v[208:211], v[8:11]
	v_mfma_f32_16x16x32_bf16 v[76:79], v[36:39], v[184:187], v[76:79]
	v_mfma_f32_16x16x32_bf16 v[72:75], v[44:47], v[184:187], v[72:75]
	v_mfma_f32_16x16x32_bf16 v[60:63], v[36:39], v[196:199], v[60:63]
	v_mfma_f32_16x16x32_bf16 v[56:59], v[44:47], v[196:199], v[56:59]
	v_mfma_f32_16x16x32_bf16 v[28:31], v[36:39], v[204:207], v[28:31]
	v_mfma_f32_16x16x32_bf16 v[24:27], v[44:47], v[204:207], v[24:27]
	v_mfma_f32_16x16x32_bf16 v[12:15], v[36:39], v[234:237], v[12:15]
	v_mfma_f32_16x16x32_bf16 v[8:11], v[44:47], v[234:237], v[8:11]
	s_setprio 0
	s_setprio 1
	v_mfma_f32_16x16x32_bf16 v[20:23], v[160:163], v[200:203], v[20:23]
	v_mfma_f32_16x16x32_bf16 v[16:19], v[168:171], v[200:203], v[16:19]
	v_mfma_f32_16x16x32_bf16 v[4:7], v[160:163], v[208:211], v[4:7]
	v_mfma_f32_16x16x32_bf16 v[0:3], v[168:171], v[208:211], v[0:3]
	v_mfma_f32_16x16x32_bf16 v[32:35], v[160:163], v[180:183], v[68:71]
	v_mfma_f32_16x16x32_bf16 v[36:39], v[168:171], v[180:183], v[64:67]
	v_mfma_f32_16x16x32_bf16 v[40:43], v[160:163], v[188:191], v[52:55]
	v_mfma_f32_16x16x32_bf16 v[44:47], v[168:171], v[188:191], v[48:51]
	v_mfma_f32_16x16x32_bf16 v[20:23], v[164:167], v[204:207], v[20:23]
	v_mfma_f32_16x16x32_bf16 v[16:19], v[176:179], v[204:207], v[16:19]
	v_mfma_f32_16x16x32_bf16 v[4:7], v[164:167], v[234:237], v[4:7]
	v_mfma_f32_16x16x32_bf16 v[0:3], v[176:179], v[234:237], v[0:3]
	v_mfma_f32_16x16x32_bf16 v[32:35], v[164:167], v[184:187], v[32:35]
	v_mfma_f32_16x16x32_bf16 v[36:39], v[176:179], v[184:187], v[36:39]
	v_mfma_f32_16x16x32_bf16 v[40:43], v[164:167], v[196:199], v[40:43]
	v_mfma_f32_16x16x32_bf16 v[44:47], v[176:179], v[196:199], v[44:47]
	s_setprio 0
	s_barrier
; #define PG8_STAGE(bufoff, gbase, voff) do { _Pragma("unroll") for (int _i = 0; _i < 2; ++_i) \
;         __builtin_amdgcn_global_load_lds((const unsigned*)((const char*)(gbase) + (voff)[_i]), (PG8_LAS unsigned*)(lds + (bufoff) + ldsw + _i * 8192), 16, 0, 0); } while (0)
; #define PG8_LDA(dst, b, h) do { _Pragma("unroll") for (int m = 0; m < 4; ++m) _Pragma("unroll") for (int k = 0; k < 2; ++k) dst[m][k] = *(const PG8_LAS bf16x8*)(lds + PG8_SA(b, h) + aoff + m * 2048 + k * 1024); } while (0)
; #define PG8_LDB(dst, b, h) do { _Pragma("unroll") for (int n = 0; n < 2; ++n) _Pragma("unroll") for (int k = 0; k < 2; ++k) dst[n][k] = *(const PG8_LAS bf16x8*)(lds + PG8_SB(b, h) + boff + n * 2048 + k * 1024); } while (0)
; #define PG8_MMA(ai, bj, At, Bt) do { __builtin_amdgcn_s_setprio(1); _Pragma("unroll") for (int m = 0; m < 4; ++m) _Pragma("unroll") for (int n = 0; n < 2; ++n) _Pragma("unroll") for (int k = 0; k < 2; ++k) \
;         acc[ai][bj][m][n] = __builtin_amdgcn_mfma_f32_16x16x32_bf16(Bt[n][k], At[m][k], acc[ai][bj][m][n], 0, 0, 0); __builtin_amdgcn_s_setprio(0); } while (0)
; #define PG8_WAIT_V(n) asm volatile("s_waitcnt vmcnt(" #n ")" ::: "memory")
; #define PG8_WAIT_L(n) asm volatile("s_waitcnt lgkmcnt(" #n ")" ::: "memory")
; #define PG8_BAR __builtin_amdgcn_s_barrier()
; #define PG8_SCHED __builtin_amdgcn_sched_barrier(0)
; template <class Epi, class Sched, bool ALIGN_EPI = false, bool SP2 = false>
; __device__ __forceinline__ void gemm_phase(PG8_LAS unsigned char* lds, const Gemm g, const Sched& S, const Epi& E) {
;     ...
;         for (int t = 0; t < nt; t += 2) {
;             const bool last = (t == nt - 2);
;             const char* a1 = cA + (size_t)(t + 1) * kstep;
;             const char* a2 = last ? nA : cA + (size_t)(t + 2) * kstep; const char* b2 = last ? nB : cB + (size_t)(t + 2) * kstep;
;     ...
;             PG8_LDB(B0, 1, 0); PG8_LDB(B1, 1, 1); PG8_SCHED; PG8_LDA(At, 1, 0); PG8_STAGE(PG8_SA(0, 1), a2 + hstep, voffA);
;             PG8_WAIT_V(8); PG8_WAIT_L(0); PG8_BAR; PG8_MMA(0, 0, At, B0); PG8_MMA(0, 1, At, B1); PG8_BAR; PG8_SCHED;
;             PG8_LDA(At, 1, 1); PG8_STAGE(PG8_SB(1, 0), b3, voffB); PG8_STAGE(PG8_SB(1, 1), b3 + hstep, voffB); PG8_STAGE(PG8_SA(1, 0), a3, voffA);
;             PG8_WAIT_V(8); PG8_WAIT_L(0); PG8_BAR; PG8_MMA(1, 0, At, B0); PG8_MMA(1, 1, At, B1); PG8_BAR; PG8_SCHED;
	s_add_i32 s72, 0, 0x18000
	s_add_i32 s73, 0, 0x1c000
	s_add_u32 s28, s48, 0x80000
	s_addc_u32 s29, s49, 0
	s_mov_b32 m0, s80
	ds_read_b128 v[48:51], v212
	global_load_lds_dwordx4 v150, s[28:29]
	ds_read_b128 v[52:55], v212 offset:1024
	ds_read_b128 v[64:67], v212 offset:2048
	ds_read_b128 v[68:71], v212 offset:3072
	ds_read_b128 v[160:163], v213
	ds_read_b128 v[164:167], v213 offset:1024
	ds_read_b128 v[168:171], v213 offset:2048
	ds_read_b128 v[176:179], v213 offset:3072
	s_mov_b32 m0, s12
	ds_read_b128 v[180:183], v174 offset:32768
	global_load_lds_dwordx4 v146, s[28:29]
	ds_read_b128 v[184:187], v174 offset:33792
	ds_read_b128 v[188:191], v174 offset:34816
	ds_read_b128 v[196:199], v174 offset:35840
	ds_read_b128 v[200:203], v174 offset:36864
	ds_read_b128 v[204:207], v174 offset:37888
	ds_read_b128 v[208:211], v174 offset:38912
	ds_read_b128 v[234:237], v174 offset:39936
	s_waitcnt vmcnt(8)
	s_waitcnt lgkmcnt(0)
	s_barrier
	s_setprio 1
	s_waitcnt lgkmcnt(0)
	v_mfma_f32_16x16x32_bf16 v[140:143], v[48:51], v[180:183], v[140:143]
	v_mfma_f32_16x16x32_bf16 v[136:139], v[64:67], v[180:183], v[136:139]
	v_mfma_f32_16x16x32_bf16 v[124:127], v[48:51], v[188:191], v[124:127]
	v_mfma_f32_16x16x32_bf16 v[120:123], v[64:67], v[188:191], v[120:123]
	v_mfma_f32_16x16x32_bf16 v[108:111], v[48:51], v[200:203], v[108:111]
	v_mfma_f32_16x16x32_bf16 v[104:107], v[64:67], v[200:203], v[104:107]
	v_mfma_f32_16x16x32_bf16 v[92:95], v[48:51], v[208:211], v[92:95]
	v_mfma_f32_16x16x32_bf16 v[88:91], v[64:67], v[208:211], v[88:91]
	v_mfma_f32_16x16x32_bf16 v[140:143], v[52:55], v[184:187], v[140:143]
	v_mfma_f32_16x16x32_bf16 v[136:139], v[68:71], v[184:187], v[136:139]
	v_mfma_f32_16x16x32_bf16 v[124:127], v[52:55], v[196:199], v[124:127]
	v_mfma_f32_16x16x32_bf16 v[120:123], v[68:71], v[196:199], v[120:123]
	v_mfma_f32_16x16x32_bf16 v[108:111], v[52:55], v[204:207], v[108:111]
	v_mfma_f32_16x16x32_bf16 v[104:107], v[68:71], v[204:207], v[104:107]
	v_mfma_f32_16x16x32_bf16 v[92:95], v[52:55], v[234:237], v[92:95]
	v_mfma_f32_16x16x32_bf16 v[88:91], v[68:71], v[234:237], v[88:91]
	s_setprio 0
	s_setprio 1
	v_mfma_f32_16x16x32_bf16 v[132:135], v[160:163], v[180:183], v[132:135]
	v_mfma_f32_16x16x32_bf16 v[128:131], v[168:171], v[180:183], v[128:131]
	v_mfma_f32_16x16x32_bf16 v[116:119], v[160:163], v[188:191], v[116:119]
	v_mfma_f32_16x16x32_bf16 v[112:115], v[168:171], v[188:191], v[112:115]
	v_mfma_f32_16x16x32_bf16 v[100:103], v[160:163], v[200:203], v[100:103]
	v_mfma_f32_16x16x32_bf16 v[96:99], v[168:171], v[200:203], v[96:99]
	v_mfma_f32_16x16x32_bf16 v[84:87], v[160:163], v[208:211], v[84:87]
	v_mfma_f32_16x16x32_bf16 v[80:83], v[168:171], v[208:211], v[80:83]
	v_mfma_f32_16x16x32_bf16 v[132:135], v[164:167], v[184:187], v[132:135]
	v_mfma_f32_16x16x32_bf16 v[128:131], v[176:179], v[184:187], v[128:131]
	v_mfma_f32_16x16x32_bf16 v[116:119], v[164:167], v[196:199], v[116:119]
	v_mfma_f32_16x16x32_bf16 v[112:115], v[176:179], v[196:199], v[112:115]
	v_mfma_f32_16x16x32_bf16 v[100:103], v[164:167], v[204:207], v[100:103]
	v_mfma_f32_16x16x32_bf16 v[96:99], v[176:179], v[204:207], v[96:99]
	v_mfma_f32_16x16x32_bf16 v[84:87], v[164:167], v[234:237], v[84:87]
	v_mfma_f32_16x16x32_bf16 v[80:83], v[176:179], v[234:237], v[80:83]
	s_setprio 0
	s_barrier
	s_add_i32 s28, s72, s76
	s_add_u32 s98, s46, 0x80
	s_addc_u32 s99, s47, 0
	s_mov_b32 m0, s28
	ds_read_b128 v[180:183], v174 offset:49152
	global_load_lds_dwordx4 v148, s[98:99]
	s_add_i32 m0, s28, 0x2000
	s_add_u32 s28, s46, 0x80080
	s_addc_u32 s29, s47, 0
	s_add_i32 s46, s73, s76
	ds_read_b128 v[184:187], v174 offset:50176
	global_load_lds_dwordx4 v144, s[98:99]
	s_mov_b32 m0, s46
	s_add_u32 s100, s48, 0x80
	s_addc_u32 s101, s49, 0
	ds_read_b128 v[188:191], v174 offset:51200
	global_load_lds_dwordx4 v148, s[28:29]
	s_add_i32 m0, s46, 0x2000
	ds_read_b128 v[196:199], v174 offset:52224
	global_load_lds_dwordx4 v144, s[28:29]
	s_mov_b32 m0, s78
	ds_read_b128 v[200:203], v174 offset:53248
	global_load_lds_dwordx4 v150, s[100:101]
	s_mov_b32 m0, s86
	ds_read_b128 v[204:207], v174 offset:54272
	global_load_lds_dwordx4 v146, s[100:101]
	ds_read_b128 v[208:211], v174 offset:55296
	ds_read_b128 v[234:237], v174 offset:56320
	s_waitcnt vmcnt(8)
	s_waitcnt lgkmcnt(0)
	s_barrier
	s_setprio 1
	s_waitcnt lgkmcnt(0)
	v_mfma_f32_16x16x32_bf16 v[76:79], v[48:51], v[180:183], v[76:79]
	v_mfma_f32_16x16x32_bf16 v[72:75], v[64:67], v[180:183], v[72:75]
	v_mfma_f32_16x16x32_bf16 v[60:63], v[48:51], v[188:191], v[60:63]
	v_mfma_f32_16x16x32_bf16 v[56:59], v[64:67], v[188:191], v[56:59]
	v_mfma_f32_16x16x32_bf16 v[28:31], v[48:51], v[200:203], v[28:31]
	v_mfma_f32_16x16x32_bf16 v[24:27], v[64:67], v[200:203], v[24:27]
	v_mfma_f32_16x16x32_bf16 v[12:15], v[48:51], v[208:211], v[12:15]
	v_mfma_f32_16x16x32_bf16 v[8:11], v[64:67], v[208:211], v[8:11]
	v_mfma_f32_16x16x32_bf16 v[76:79], v[52:55], v[184:187], v[76:79]
	v_mfma_f32_16x16x32_bf16 v[72:75], v[68:71], v[184:187], v[72:75]
	v_mfma_f32_16x16x32_bf16 v[60:63], v[52:55], v[196:199], v[60:63]
	v_mfma_f32_16x16x32_bf16 v[56:59], v[68:71], v[196:199], v[56:59]
	v_mfma_f32_16x16x32_bf16 v[28:31], v[52:55], v[204:207], v[28:31]
	v_mfma_f32_16x16x32_bf16 v[24:27], v[68:71], v[204:207], v[24:27]
	v_mfma_f32_16x16x32_bf16 v[12:15], v[52:55], v[234:237], v[12:15]
	v_mfma_f32_16x16x32_bf16 v[8:11], v[68:71], v[234:237], v[8:11]
	s_setprio 0
	s_setprio 1
	v_mfma_f32_16x16x32_bf16 v[32:35], v[160:163], v[180:183], v[32:35]
	v_mfma_f32_16x16x32_bf16 v[68:71], v[164:167], v[184:187], v[32:35]
	v_mfma_f32_16x16x32_bf16 v[32:35], v[168:171], v[180:183], v[36:39]
	v_mfma_f32_16x16x32_bf16 v[64:67], v[176:179], v[184:187], v[32:35]
	v_mfma_f32_16x16x32_bf16 v[32:35], v[160:163], v[188:191], v[40:43]
	v_mfma_f32_16x16x32_bf16 v[52:55], v[164:167], v[196:199], v[32:35]
	v_mfma_f32_16x16x32_bf16 v[32:35], v[168:171], v[188:191], v[44:47]
	v_mfma_f32_16x16x32_bf16 v[20:23], v[160:163], v[200:203], v[20:23]
	v_mfma_f32_16x16x32_bf16 v[16:19], v[168:171], v[200:203], v[16:19]
	v_mfma_f32_16x16x32_bf16 v[4:7], v[160:163], v[208:211], v[4:7]
	v_mfma_f32_16x16x32_bf16 v[0:3], v[168:171], v[208:211], v[0:3]
	v_mfma_f32_16x16x32_bf16 v[48:51], v[176:179], v[196:199], v[32:35]
	v_mfma_f32_16x16x32_bf16 v[20:23], v[164:167], v[204:207], v[20:23]
	v_mfma_f32_16x16x32_bf16 v[16:19], v[176:179], v[204:207], v[16:19]
	v_mfma_f32_16x16x32_bf16 v[4:7], v[164:167], v[234:237], v[4:7]
	v_mfma_f32_16x16x32_bf16 v[0:3], v[176:179], v[234:237], v[0:3]
	s_setprio 0
	s_barrier
	s_add_i32 s88, s88, 2
	s_add_u32 s26, s26, 0x100
	s_addc_u32 s27, s27, 0
	s_add_u32 s55, s55, 0x100
	s_addc_u32 s61, s61, 0
	s_cmp_gt_u32 s88, 29
	s_cbranch_scc0 .LBB0_402
	s_and_b64 vcc, exec, s[22:23]
	s_cbranch_vccz .LBB0_405
	s_barrier
